# v15 + P9 indexer key-tile prefetch: both halves of next stage loaded at item top (second half in v240-247), full item of latency cover
# speedup vs baseline: 1.0023x; 1.0023x over previous
; #define LAS __attribute__((address_space(3)))
; #define IX_PF_LOAD(h_) do { if (more) { _Pragma("unroll") for (int it = 0; it < 2; ++it) { const int ci = tid + 512 * (2 * (h_) + it), row = ci >> 4, ch = ci & 15; st[it] = *(const v4u*)(KIB + (size_t)(128 * ns + row) * 128 + 8 * ch); } } } while (0)
; DI void indexer_prompt(LAS unsigned char* lds, const bf16* QIB, const bf16* KIB, const float* WI, float* SC, int bid, int G, int tid_) {
;     ...
;         int nqb = qb, ns = s + 1; if (ns > (qb >> 1)) { nqb = qb + 1; ns = 0; }
;         const bool more = item + 1 < hi;
;         v4u st[2];
;         LAS unsigned char* NBUF = lds + IX_ST0 + (((item - lo) & 1) ^ 1) * IX_STB;
;     ...
;         IX_PF_LOAD(0);
;         f32x2 wn = (f32x2){0.f, 0.f};
;         if (more && nqb != qb) wn = *(const f32x2*)(WI + (size_t)(64 * nqb) * 16 + 2 * tid);
.LBB0_1507:
	s_add_i32 s12, s18, 1
	s_lshr_b32 s14, s30, 1
	s_cmp_ge_i32 s18, s14
	s_cselect_b64 s[14:15], -1, 0
	s_and_b64 s[16:17], s[14:15], exec
	s_cselect_b32 s38, 0, s12
	s_cmp_lg_u64 s[14:15], 0
	s_addc_u32 s30, s30, 0
	s_add_i32 s12, s4, s35
	s_add_i32 s12, s12, 1
	v_cndmask_b32_e64 v1, 0, 1, s[14:15]
	s_cmp_lt_i32 s12, s5
	v_lshlrev_b32_e32 v168, 3, v171
	v_readfirstlane_b32 s39, v1
	s_cselect_b64 s[16:17], -1, 0
	s_lshl_b32 s40, s38, 7
	v_and_b32_e32 v1, 0x78, v168
	s_cmp_ge_i32 s12, s5
	s_waitcnt vmcnt(0)
	v_mov_b32_e32 v154, 0
	v_add_u32_e32 v172, 0x200, v171
	v_lshlrev_b32_e32 v164, 1, v1
	v_mov_b32_e32 v155, 0
	s_cbranch_scc1 .LBB0_1510
	v_ashrrev_i32_e32 v1, 4, v171
	v_add_u32_e32 v4, s40, v1
	v_ashrrev_i32_e32 v1, 4, v172
	v_mov_b32_e32 v165, v153
	v_ashrrev_i32_e32 v5, 31, v4
	v_add_u32_e32 v6, s40, v1
	v_lshl_add_u64 v[2:3], s[6:7], 0, v[164:165]
	v_lshlrev_b64 v[4:5], 8, v[4:5]
	v_ashrrev_i32_e32 v7, 31, v6
	v_lshl_add_u64 v[4:5], v[2:3], 0, v[4:5]
	v_lshlrev_b64 v[6:7], 8, v[6:7]
	v_lshl_add_u64 v[2:3], v[2:3], 0, v[6:7]
	global_load_dwordx4 v[116:119], v[4:5], off
	global_load_dwordx4 v[112:115], v[2:3], off
	s_mov_b64 s[100:101], 0x4000
	v_lshl_add_u64 v[6:7], v[4:5], 0, s[100:101]
	v_lshl_add_u64 v[4:5], v[2:3], 0, s[100:101]
	global_load_dwordx4 v[240:243], v[6:7], off
	global_load_dwordx4 v[244:247], v[4:5], off
	v_mov_b32_e32 v155, 0
	s_andn2_b64 vcc, exec, s[14:15]
	v_mov_b32_e32 v154, 0
	s_cbranch_vccnz .LBB0_1510
	s_lshl_b32 s12, s30, 6
	s_lshl_b64 s[20:21], s[12:13], 6
	s_add_u32 s20, s3, s20
	v_lshlrev_b32_e32 v2, 1, v171
	s_addc_u32 s21, s29, s21
	v_ashrrev_i32_e32 v3, 31, v2
	v_lshl_add_u64 v[2:3], v[2:3], 2, s[20:21]
	global_load_dwordx2 v[154:155], v[2:3], off

; #define LAS __attribute__((address_space(3)))
; #define IX_PF_LOAD(h_) do { if (more) { _Pragma("unroll") for (int it = 0; it < 2; ++it) { const int ci = tid + 512 * (2 * (h_) + it), row = ci >> 4, ch = ci & 15; st[it] = *(const v4u*)(KIB + (size_t)(128 * ns + row) * 128 + 8 * ch); } } } while (0)
; #define IX_PF_STORE(h_) do { if (more) { _Pragma("unroll") for (int it = 0; it < 2; ++it) { const int ci = tid + 512 * (2 * (h_) + it), row = ci >> 4, ch = ci & 15; *(LAS v4u*)(NBUF + row * 272 + 16 * ch) = st[it]; } } } while (0)
; DI void indexer_prompt(LAS unsigned char* lds, const bf16* QIB, const bf16* KIB, const float* WI, float* SC, int bid, int G, int tid_) {
;     ...
;         LAS unsigned char* NBUF = lds + IX_ST0 + (((item - lo) & 1) ^ 1) * IX_STB;
;     ...
;             if (bt == 2) { IX_PF_STORE(0); IX_PF_LOAD(1); }
.LBB0_1514:
	s_xor_b32 s21, s41, 1
	s_mul_i32 s21, s21, 0x8800
	v_lshlrev_b32_e32 v0, 4, v171
	s_add_i32 s21, s21, 0
	v_and_b32_e32 v0, 0xf0, v0
	v_add_u32_e32 v152, s21, v0
	v_add_u32_e32 v173, 0x400, v171
	s_andn2_b64 vcc, exec, s[16:17]
	v_add_u32_e32 v174, 0x600, v171
	s_cbranch_vccnz .LBB0_1518
	v_lshrrev_b32_e32 v2, 4, v171
	v_mad_u64_u32 v[2:3], s[22:23], v2, s34, v[152:153]
	s_cmp_eq_u32 s100, 1
	s_cbranch_scc1 .Lmy_p9w1
	s_waitcnt vmcnt(3)
.Lmy_p9w1:
	s_waitcnt vmcnt(11)
	ds_write_b128 v2, v[116:119] offset:4096
	v_lshrrev_b32_e32 v2, 4, v172
	v_mad_u64_u32 v[2:3], s[22:23], v2, s34, v[152:153]
	s_cmp_eq_u32 s100, 1
	s_cbranch_scc1 .Lmy_p9w2
	s_waitcnt vmcnt(2)
.Lmy_p9w2:
	s_waitcnt vmcnt(10)
	ds_write_b128 v2, v[112:115] offset:4096
	s_or_b32 s21, s20, 64
	s_cmp_gt_i32 s21, s12
	s_cbranch_scc0 .LBB0_1519

; #define LAS __attribute__((address_space(3)))
; #define IX_PF_STORE(h_) do { if (more) { _Pragma("unroll") for (int it = 0; it < 2; ++it) { const int ci = tid + 512 * (2 * (h_) + it), row = ci >> 4, ch = ci & 15; *(LAS v4u*)(NBUF + row * 272 + 16 * ch) = st[it]; } } } while (0)
; DI void indexer_prompt(LAS unsigned char* lds, const bf16* QIB, const bf16* KIB, const float* WI, float* SC, int bid, int G, int tid_) {
;     ...
;         IX_PF_STORE(1);
;     ...
;         if (more) {
;             if (nqb != qb) *(LAS f32x2*)(lds + (wsel ? IX_W : IX_W2) + 8 * tid) = wn;
;         }
.Lmy_p9w3:
	s_waitcnt vmcnt(9)
	ds_write_b128 v0, v[240:243] offset:4096
	v_lshrrev_b32_e32 v0, 4, v174
	v_mad_u64_u32 v[0:1], s[16:17], v0, s34, v[152:153]
	s_and_b64 vcc, exec, s[14:15]
	s_cmp_eq_u32 s101, 1
	s_cbranch_scc1 .Lmy_p9w4
	s_waitcnt vmcnt(0)
.Lmy_p9w4:
	s_waitcnt vmcnt(8)
	ds_write_b128 v0, v[244:247] offset:4096
	s_cbranch_vccz .LBB0_1504
	s_and_b64 s[16:17], s[18:19], exec
	s_cselect_b32 s12, 0x12000, 0
	s_add_i32 s12, s12, 0
	v_add_u32_e32 v0, s12, v168
	ds_write_b64 v0, v[154:155]
	s_branch .LBB0_1504
